# GEMM epilogues of E1 / O1 / Q-up / K-up: each 8-byte store (address and data) moved by ds_bpermute to a lane order where a quad writes 32 contiguous bytes; stores issued one slot late to hide the LDS
# speedup vs baseline: 1.0596x; 1.0173x over previous
; template <int EPI, int TI>
; __device__ __forceinline__ void gemm_epilogue(const WS& ws, const f32x4 (&acc)[4][TI], const float (&rs)[TI], int tok0, int n0,
;                                               int wm, int wn, int lr, int lq, bool dry) {
;     ...
;   if (EPI == EPI_E1) {
;     bf16_t* dst; int ld, c;
;     if (n0 < 1024) { dst = ws.XA; ld = 1024; c = n0; }
;     else if (n0 < 2048) { dst = ws.GA; ld = 1024; c = n0 - 1024; }
;     else if (n0 < 2560) { dst = ws.Q; ld = 512; c = n0 - 2048; }
;     else if (n0 < 3072) { dst = ws.K; ld = 512; c = n0 - 2560; }
;     else if (n0 < 4096) { dst = ws.V; ld = 1024; c = n0 - 3072; }
;     else if (n0 < 5120) { dst = ws.GB; ld = 1024; c = n0 - 4096; }
;     else { dst = ws.AD; ld = 16; c = 0; }
;     const bool isad = n0 >= 5120;
; #pragma unroll
;     for (int ni = 0; ni < 4; ++ni) {
;       if (isad && (wm != 0 || ni != 0)) continue;
; #pragma unroll
;       for (int ti = 0; ti < TI; ++ti) {
;         const f32x4 v = scale4(acc[ni][ti], rs[ti]);
;         u32x2 pk; pk.x = cvt_pk_bf16(v[0], v[1]); pk.y = cvt_pk_bf16(v[2], v[3]);
;         if (okr(ti)) *(u32x2*)(dst + (size_t)tokr(ti) * ld + c + wm * 64 + ni * 16 + 4 * lq) = pk;
;       }
;     }
.LBB0_625:
	v_mbcnt_lo_u32_b32 v250, -1, 0
	v_mbcnt_hi_u32_b32 v250, -1, v250
	v_and_b32_e32 v251, 3, v250
	v_lshrrev_b32_e32 v250, 2, v250
	v_lshl_add_u32 v250, v251, 4, v250
	v_lshlrev_b32_e32 v250, 2, v250
	v_add_u32_e32 v13, s7, v147
	s_ashr_i32 s7, s6, 31
	s_lshl_b64 s[6:7], s[6:7], 1
	s_add_u32 s6, s12, s6
	s_waitcnt lgkmcnt(1)
	v_mov_b32_e32 v115, v132
	s_addc_u32 s7, s13, s7
	v_lshl_add_u64 v[134:135], v[118:119], 1, s[6:7]
	v_mul_f32_e32 v110, v110, v115
	v_mul_f32_e32 v111, v111, v115
	v_mul_f32_e32 v112, v112, v115
	v_mul_f32_e32 v113, v113, v115
	v_mov_b32_e32 v125, v12
	v_lshl_add_u64 v[134:135], v[134:135], 0, v[124:125]
	v_cvt_pk_bf16_f32 v110, v110, v111
	v_cvt_pk_bf16_f32 v111, v112, v113
	v_mad_i64_i32 v[112:113], s[6:7], s4, v13, 0
	v_lshl_add_u64 v[112:113], v[112:113], 1, v[134:135]
	ds_bpermute_b32 v242, v250, v112
	ds_bpermute_b32 v243, v250, v113
	ds_bpermute_b32 v252, v250, v110
	ds_bpermute_b32 v253, v250, v111
	v_mov_b32_e32 v110, v133
	s_nop 0
	v_mul_f32_e32 v106, v106, v110
	v_mul_f32_e32 v107, v107, v110
	v_mul_f32_e32 v108, v108, v110
	v_mul_f32_e32 v109, v109, v110
	s_nop 0
	v_cvt_pk_bf16_f32 v106, v106, v107
	v_cvt_pk_bf16_f32 v107, v108, v109
	v_add_u32_e32 v108, 16, v13
	v_mad_i64_i32 v[108:109], s[6:7], s4, v108, 0
	v_lshl_add_u64 v[108:109], v[108:109], 1, v[134:135]
	ds_bpermute_b32 v244, v250, v108
	ds_bpermute_b32 v245, v250, v109
	ds_bpermute_b32 v254, v250, v106
	ds_bpermute_b32 v255, v250, v107
	s_waitcnt lgkmcnt(4)
	global_store_dwordx2 v[242:243], v[252:253], off
	s_waitcnt lgkmcnt(0)
	v_mov_b32_e32 v106, v130
	s_nop 0
	v_mul_f32_e32 v102, v102, v106
	v_mul_f32_e32 v103, v103, v106
	v_mul_f32_e32 v104, v104, v106
	v_mul_f32_e32 v105, v105, v106
	s_nop 0
	v_cvt_pk_bf16_f32 v102, v102, v103
	v_cvt_pk_bf16_f32 v103, v104, v105
	v_add_u32_e32 v104, 32, v13
	v_mad_i64_i32 v[104:105], s[6:7], s4, v104, 0
	v_lshl_add_u64 v[104:105], v[104:105], 1, v[134:135]
	ds_bpermute_b32 v246, v250, v104
	ds_bpermute_b32 v247, v250, v105
	ds_bpermute_b32 v252, v250, v102
	ds_bpermute_b32 v253, v250, v103
	s_waitcnt lgkmcnt(4)
	global_store_dwordx2 v[244:245], v[254:255], off
	v_mov_b32_e32 v102, v131
	v_add_u32_e32 v13, 48, v13
	v_mul_f32_e32 v98, v98, v102
	v_mul_f32_e32 v99, v99, v102
	v_mul_f32_e32 v100, v100, v102
	v_mul_f32_e32 v101, v101, v102
	s_nop 0
	v_cvt_pk_bf16_f32 v98, v98, v99
	v_cvt_pk_bf16_f32 v99, v100, v101
	v_mad_i64_i32 v[100:101], s[4:5], s4, v13, 0
	v_lshl_add_u64 v[100:101], v[100:101], 1, v[134:135]
	v_mov_b32_e32 v13, v132
	ds_bpermute_b32 v248, v250, v100
	ds_bpermute_b32 v249, v250, v101
	ds_bpermute_b32 v254, v250, v98
	ds_bpermute_b32 v255, v250, v99
	s_waitcnt lgkmcnt(4)
	global_store_dwordx2 v[246:247], v[252:253], off
	s_nop 0
	v_mul_f32_e32 v94, v94, v13
	v_mul_f32_e32 v95, v95, v13
	v_mul_f32_e32 v96, v96, v13
	v_mul_f32_e32 v13, v97, v13
	s_nop 0
	v_cvt_pk_bf16_f32 v94, v94, v95
	v_cvt_pk_bf16_f32 v95, v96, v13
	v_mov_b32_e32 v13, v133
	ds_bpermute_b32 v252, v250, v94
	ds_bpermute_b32 v253, v250, v95
	s_waitcnt lgkmcnt(2)
	global_store_dwordx2 v[248:249], v[254:255], off
	s_nop 0
	v_mul_f32_e32 v90, v90, v13
	v_mul_f32_e32 v91, v91, v13
	v_mul_f32_e32 v92, v92, v13
	v_mul_f32_e32 v13, v93, v13
	s_nop 0
	v_cvt_pk_bf16_f32 v90, v90, v91
	v_cvt_pk_bf16_f32 v91, v92, v13
	v_mov_b32_e32 v13, v130
	ds_bpermute_b32 v254, v250, v90
	ds_bpermute_b32 v255, v250, v91
	s_waitcnt lgkmcnt(2)
; template <int EPI, int TI>
; __device__ __forceinline__ void gemm_epilogue(const WS& ws, const f32x4 (&acc)[4][TI], const float (&rs)[TI], int tok0, int n0,
;                                               int wm, int wn, int lr, int lq, bool dry) {
;     ...
; #pragma unroll
;     for (int ni = 0; ni < 4; ++ni) {
;       if (isad && (wm != 0 || ni != 0)) continue;
; #pragma unroll
;       for (int ti = 0; ti < TI; ++ti) {
;         const f32x4 v = scale4(acc[ni][ti], rs[ti]);
;         u32x2 pk; pk.x = cvt_pk_bf16(v[0], v[1]); pk.y = cvt_pk_bf16(v[2], v[3]);
;         if (okr(ti)) *(u32x2*)(dst + (size_t)tokr(ti) * ld + c + wm * 64 + ni * 16 + 4 * lq) = pk;
;       }
;     }
	global_store_dwordx2 v[242:243], v[252:253], off offset:32
	s_nop 0
	v_mul_f32_e32 v86, v86, v13
	v_mul_f32_e32 v87, v87, v13
	v_mul_f32_e32 v88, v88, v13
	v_mul_f32_e32 v13, v89, v13
	s_nop 0
	v_cvt_pk_bf16_f32 v86, v86, v87
	v_cvt_pk_bf16_f32 v87, v88, v13
	v_mov_b32_e32 v13, v131
	ds_bpermute_b32 v252, v250, v86
	ds_bpermute_b32 v253, v250, v87
	s_waitcnt lgkmcnt(2)
	global_store_dwordx2 v[244:245], v[254:255], off offset:32
	s_nop 0
	v_mul_f32_e32 v82, v82, v13
	v_mul_f32_e32 v83, v83, v13
	v_mul_f32_e32 v84, v84, v13
	v_mul_f32_e32 v13, v85, v13
	s_nop 0
	v_cvt_pk_bf16_f32 v82, v82, v83
	v_cvt_pk_bf16_f32 v83, v84, v13
	v_mov_b32_e32 v13, v132
	ds_bpermute_b32 v254, v250, v82
	ds_bpermute_b32 v255, v250, v83
	s_waitcnt lgkmcnt(2)
	global_store_dwordx2 v[246:247], v[252:253], off offset:32
	s_nop 0
	v_mul_f32_e32 v78, v78, v13
	v_mul_f32_e32 v79, v79, v13
	v_mul_f32_e32 v80, v80, v13
	v_mul_f32_e32 v13, v81, v13
	s_nop 0
	v_cvt_pk_bf16_f32 v78, v78, v79
	v_cvt_pk_bf16_f32 v79, v80, v13
	v_mov_b32_e32 v13, v133
	ds_bpermute_b32 v252, v250, v78
	ds_bpermute_b32 v253, v250, v79
	s_waitcnt lgkmcnt(2)
	global_store_dwordx2 v[248:249], v[254:255], off offset:32
	s_nop 0
	v_mul_f32_e32 v74, v74, v13
	v_mul_f32_e32 v75, v75, v13
	v_mul_f32_e32 v76, v76, v13
	v_mul_f32_e32 v13, v77, v13
	s_nop 0
	v_cvt_pk_bf16_f32 v74, v74, v75
	v_cvt_pk_bf16_f32 v75, v76, v13
	v_mov_b32_e32 v13, v130
	ds_bpermute_b32 v254, v250, v74
	ds_bpermute_b32 v255, v250, v75
	s_waitcnt lgkmcnt(2)
	global_store_dwordx2 v[242:243], v[252:253], off offset:64
	s_nop 0
	v_mul_f32_e32 v70, v70, v13
	v_mul_f32_e32 v71, v71, v13
	v_mul_f32_e32 v72, v72, v13
	v_mul_f32_e32 v13, v73, v13
	s_nop 0
	v_cvt_pk_bf16_f32 v70, v70, v71
	v_cvt_pk_bf16_f32 v71, v72, v13
	v_mov_b32_e32 v13, v131
	ds_bpermute_b32 v252, v250, v70
	ds_bpermute_b32 v253, v250, v71
	s_waitcnt lgkmcnt(2)
	global_store_dwordx2 v[244:245], v[254:255], off offset:64
	s_nop 0
	v_mul_f32_e32 v66, v66, v13
	v_mul_f32_e32 v67, v67, v13
	v_mul_f32_e32 v68, v68, v13
	v_mul_f32_e32 v13, v69, v13
	s_nop 0
	v_cvt_pk_bf16_f32 v66, v66, v67
	v_cvt_pk_bf16_f32 v67, v68, v13
	ds_bpermute_b32 v254, v250, v66
	ds_bpermute_b32 v255, v250, v67
	s_waitcnt lgkmcnt(2)
	global_store_dwordx2 v[246:247], v[252:253], off offset:64
	s_nop 0
	v_mul_f32_e32 v13, v62, v132
	v_mul_f32_e32 v62, v63, v132
	v_mul_f32_e32 v63, v64, v132
	v_mul_f32_e32 v64, v65, v132
	s_nop 0
	v_cvt_pk_bf16_f32 v62, v13, v62
	v_cvt_pk_bf16_f32 v63, v63, v64
	ds_bpermute_b32 v252, v250, v62
	ds_bpermute_b32 v253, v250, v63
	s_waitcnt lgkmcnt(2)
	global_store_dwordx2 v[248:249], v[254:255], off offset:64
	s_nop 0
	v_mul_f32_e32 v13, v58, v133
	v_mul_f32_e32 v58, v59, v133
	v_mul_f32_e32 v59, v60, v133
	v_mul_f32_e32 v60, v61, v133
	s_nop 0
	v_cvt_pk_bf16_f32 v58, v13, v58
	v_cvt_pk_bf16_f32 v59, v59, v60
	ds_bpermute_b32 v254, v250, v58
	ds_bpermute_b32 v255, v250, v59
	s_waitcnt lgkmcnt(2)
	global_store_dwordx2 v[242:243], v[252:253], off offset:96
	s_nop 0
	v_mul_f32_e32 v13, v46, v130
	v_mul_f32_e32 v46, v47, v130
	v_mul_f32_e32 v47, v48, v130
	v_mul_f32_e32 v48, v49, v130
	s_nop 0
	v_cvt_pk_bf16_f32 v46, v13, v46
	v_cvt_pk_bf16_f32 v47, v47, v48
	ds_bpermute_b32 v252, v250, v46
	ds_bpermute_b32 v253, v250, v47
	s_waitcnt lgkmcnt(2)
	global_store_dwordx2 v[244:245], v[254:255], off offset:96
	s_nop 0
	v_mul_f32_e32 v13, v26, v131
	v_mul_f32_e32 v26, v27, v131
	v_mul_f32_e32 v27, v28, v131
	v_mul_f32_e32 v28, v29, v131
	s_nop 0
	v_cvt_pk_bf16_f32 v26, v13, v26
	v_cvt_pk_bf16_f32 v27, v27, v28
	ds_bpermute_b32 v254, v250, v26
	ds_bpermute_b32 v255, v250, v27
	s_waitcnt lgkmcnt(2)
	global_store_dwordx2 v[246:247], v[252:253], off offset:96
	s_waitcnt lgkmcnt(0)
	global_store_dwordx2 v[248:249], v[254:255], off offset:96

; __device__ __forceinline__ f32x4 scale4(f32x4 a, float r) {
;   asm volatile("" : "+v"(r));
;   float x0 = a[0] * r, x1 = a[1] * r, x2 = a[2] * r, x3 = a[3] * r;
;   asm volatile("" : "+v"(x0), "+v"(x1), "+v"(x2), "+v"(x3));
;   return (f32x4){x0, x1, x2, x3};
; }
; template <int EPI, int TI>
; __device__ __forceinline__ void gemm_epilogue(const WS& ws, const f32x4 (&acc)[4][TI], const float (&rs)[TI], int tok0, int n0,
;                                               int wm, int wn, int lr, int lq, bool dry) {
;     ...
;   } else if (EPI == EPI_Q) {
; #pragma unroll
;     for (int ni = 0; ni < 4; ++ni)
; #pragma unroll
;       for (int ti = 0; ti < TI; ++ti) {
;         const f32x4 v = scale4(acc[ni][ti], rs[ti]);
;         u32x2 pk; pk.x = cvt_pk_bf16(v[0], v[1]); pk.y = cvt_pk_bf16(v[2], v[3]);
;         if (okr(ti)) *(u32x2*)(ws.QB + (size_t)tokr(ti) * 1536 + nw + ni * 16 + 4 * lq) = pk;
;       }
.LBB0_720:
	v_mbcnt_lo_u32_b32 v250, -1, 0
	v_mbcnt_hi_u32_b32 v250, -1, v250
	v_and_b32_e32 v251, 3, v250
	v_lshrrev_b32_e32 v250, 2, v250
	v_lshl_add_u32 v250, v251, 4, v250
	v_lshlrev_b32_e32 v250, 2, v250
	s_waitcnt lgkmcnt(1)
	v_mov_b32_e32 v115, v126
	v_lshl_add_u32 v140, s10, 7, v139
	v_mul_f32_e32 v110, v110, v115
	v_mul_f32_e32 v111, v111, v115
	v_mul_f32_e32 v112, v112, v115
	v_mul_f32_e32 v113, v113, v115
	v_add_u32_e32 v13, s11, v137
	v_ashrrev_i32_e32 v141, 31, v140
	v_cvt_pk_bf16_f32 v110, v110, v111
	v_cvt_pk_bf16_f32 v111, v112, v113
	v_mov_b64_e32 v[112:113], s[42:43]
	v_mad_i64_i32 v[142:143], s[10:11], v13, s83, v[112:113]
	v_lshlrev_b64 v[140:141], 1, v[140:141]
	v_lshl_add_u64 v[142:143], v[142:143], 0, v[140:141]
	v_mov_b32_e32 v119, v12
	v_lshl_add_u64 v[142:143], v[142:143], 0, v[118:119]
	ds_bpermute_b32 v242, v250, v142
	ds_bpermute_b32 v243, v250, v143
	ds_bpermute_b32 v252, v250, v110
	ds_bpermute_b32 v253, v250, v111
	v_mov_b32_e32 v110, v127
	s_nop 0
	v_mul_f32_e32 v106, v106, v110
	v_mul_f32_e32 v107, v107, v110
	v_mul_f32_e32 v108, v108, v110
	v_mul_f32_e32 v109, v109, v110
	s_nop 0
	v_cvt_pk_bf16_f32 v106, v106, v107
	v_cvt_pk_bf16_f32 v107, v108, v109
	v_add_u32_e32 v108, 16, v13
	v_mad_i64_i32 v[108:109], s[10:11], v108, s83, v[112:113]
	v_lshl_add_u64 v[108:109], v[108:109], 0, v[140:141]
	v_lshl_add_u64 v[108:109], v[108:109], 0, v[118:119]
	ds_bpermute_b32 v244, v250, v108
	ds_bpermute_b32 v245, v250, v109
	ds_bpermute_b32 v254, v250, v106
	ds_bpermute_b32 v255, v250, v107
	s_waitcnt lgkmcnt(4)
	global_store_dwordx2 v[242:243], v[252:253], off
	s_waitcnt lgkmcnt(0)
	v_mov_b32_e32 v106, v124
	s_nop 0
	v_mul_f32_e32 v102, v102, v106
	v_mul_f32_e32 v103, v103, v106
	v_mul_f32_e32 v104, v104, v106
	v_mul_f32_e32 v105, v105, v106
	s_nop 0
	v_cvt_pk_bf16_f32 v102, v102, v103
	v_cvt_pk_bf16_f32 v103, v104, v105
	v_add_u32_e32 v104, 32, v13
	v_mad_i64_i32 v[104:105], s[10:11], v104, s83, v[112:113]
	v_lshl_add_u64 v[104:105], v[104:105], 0, v[140:141]
	v_lshl_add_u64 v[104:105], v[104:105], 0, v[118:119]
	ds_bpermute_b32 v246, v250, v104
	ds_bpermute_b32 v247, v250, v105
	ds_bpermute_b32 v252, v250, v102
	ds_bpermute_b32 v253, v250, v103
	s_waitcnt lgkmcnt(4)
	global_store_dwordx2 v[244:245], v[254:255], off
	v_mov_b32_e32 v102, v125
	v_add_u32_e32 v13, 48, v13
	v_mul_f32_e32 v98, v98, v102
	v_mul_f32_e32 v99, v99, v102
	v_mul_f32_e32 v100, v100, v102
	v_mul_f32_e32 v101, v101, v102
	s_nop 0
	v_cvt_pk_bf16_f32 v98, v98, v99
	v_cvt_pk_bf16_f32 v99, v100, v101
	v_mad_i64_i32 v[100:101], s[10:11], v13, s83, v[112:113]
	v_lshl_add_u64 v[100:101], v[100:101], 0, v[140:141]
	v_lshl_add_u64 v[100:101], v[100:101], 0, v[118:119]
	v_mov_b32_e32 v13, v126
	ds_bpermute_b32 v248, v250, v100
	ds_bpermute_b32 v249, v250, v101
	ds_bpermute_b32 v254, v250, v98
	ds_bpermute_b32 v255, v250, v99
	s_waitcnt lgkmcnt(4)
	global_store_dwordx2 v[246:247], v[252:253], off
	s_nop 0
	v_mul_f32_e32 v94, v94, v13
	v_mul_f32_e32 v95, v95, v13
	v_mul_f32_e32 v96, v96, v13
	v_mul_f32_e32 v13, v97, v13
	s_nop 0
	v_cvt_pk_bf16_f32 v94, v94, v95
	v_cvt_pk_bf16_f32 v95, v96, v13
	v_mov_b32_e32 v13, v127
	ds_bpermute_b32 v252, v250, v94
	ds_bpermute_b32 v253, v250, v95
	s_waitcnt lgkmcnt(2)
	global_store_dwordx2 v[248:249], v[254:255], off
	s_nop 0
	v_mul_f32_e32 v90, v90, v13
	v_mul_f32_e32 v91, v91, v13
	v_mul_f32_e32 v92, v92, v13
	v_mul_f32_e32 v13, v93, v13
	s_nop 0
	v_cvt_pk_bf16_f32 v90, v90, v91
	v_cvt_pk_bf16_f32 v91, v92, v13
	v_mov_b32_e32 v13, v124
	ds_bpermute_b32 v254, v250, v90
	ds_bpermute_b32 v255, v250, v91
	s_waitcnt lgkmcnt(2)
; __device__ __forceinline__ f32x4 scale4(f32x4 a, float r) {
;   asm volatile("" : "+v"(r));
;   float x0 = a[0] * r, x1 = a[1] * r, x2 = a[2] * r, x3 = a[3] * r;
;   asm volatile("" : "+v"(x0), "+v"(x1), "+v"(x2), "+v"(x3));
;   return (f32x4){x0, x1, x2, x3};
; }
; template <int EPI, int TI>
; __device__ __forceinline__ void gemm_epilogue(const WS& ws, const f32x4 (&acc)[4][TI], const float (&rs)[TI], int tok0, int n0,
;                                               int wm, int wn, int lr, int lq, bool dry) {
;     ...
;   } else if (EPI == EPI_Q) {
; #pragma unroll
;     for (int ni = 0; ni < 4; ++ni)
; #pragma unroll
;       for (int ti = 0; ti < TI; ++ti) {
;         const f32x4 v = scale4(acc[ni][ti], rs[ti]);
;         u32x2 pk; pk.x = cvt_pk_bf16(v[0], v[1]); pk.y = cvt_pk_bf16(v[2], v[3]);
;         if (okr(ti)) *(u32x2*)(ws.QB + (size_t)tokr(ti) * 1536 + nw + ni * 16 + 4 * lq) = pk;
;       }
	global_store_dwordx2 v[242:243], v[252:253], off offset:32
	s_nop 0
	v_mul_f32_e32 v86, v86, v13
	v_mul_f32_e32 v87, v87, v13
	v_mul_f32_e32 v88, v88, v13
	v_mul_f32_e32 v13, v89, v13
	s_nop 0
	v_cvt_pk_bf16_f32 v86, v86, v87
	v_cvt_pk_bf16_f32 v87, v88, v13
	v_mov_b32_e32 v13, v125
	ds_bpermute_b32 v252, v250, v86
	ds_bpermute_b32 v253, v250, v87
	s_waitcnt lgkmcnt(2)
	global_store_dwordx2 v[244:245], v[254:255], off offset:32
	s_nop 0
	v_mul_f32_e32 v82, v82, v13
	v_mul_f32_e32 v83, v83, v13
	v_mul_f32_e32 v84, v84, v13
	v_mul_f32_e32 v13, v85, v13
	s_nop 0
	v_cvt_pk_bf16_f32 v82, v82, v83
	v_cvt_pk_bf16_f32 v83, v84, v13
	v_mov_b32_e32 v13, v126
	ds_bpermute_b32 v254, v250, v82
	ds_bpermute_b32 v255, v250, v83
	s_waitcnt lgkmcnt(2)
	global_store_dwordx2 v[246:247], v[252:253], off offset:32
	s_nop 0
	v_mul_f32_e32 v78, v78, v13
	v_mul_f32_e32 v79, v79, v13
	v_mul_f32_e32 v80, v80, v13
	v_mul_f32_e32 v13, v81, v13
	s_nop 0
	v_cvt_pk_bf16_f32 v78, v78, v79
	v_cvt_pk_bf16_f32 v79, v80, v13
	v_mov_b32_e32 v13, v127
	ds_bpermute_b32 v252, v250, v78
	ds_bpermute_b32 v253, v250, v79
	s_waitcnt lgkmcnt(2)
	global_store_dwordx2 v[248:249], v[254:255], off offset:32
	s_nop 0
	v_mul_f32_e32 v74, v74, v13
	v_mul_f32_e32 v75, v75, v13
	v_mul_f32_e32 v76, v76, v13
	v_mul_f32_e32 v13, v77, v13
	s_nop 0
	v_cvt_pk_bf16_f32 v74, v74, v75
	v_cvt_pk_bf16_f32 v75, v76, v13
	v_mov_b32_e32 v13, v124
	ds_bpermute_b32 v254, v250, v74
	ds_bpermute_b32 v255, v250, v75
	s_waitcnt lgkmcnt(2)
	global_store_dwordx2 v[242:243], v[252:253], off offset:64
	s_nop 0
	v_mul_f32_e32 v70, v70, v13
	v_mul_f32_e32 v71, v71, v13
	v_mul_f32_e32 v72, v72, v13
	v_mul_f32_e32 v13, v73, v13
	s_nop 0
	v_cvt_pk_bf16_f32 v70, v70, v71
	v_cvt_pk_bf16_f32 v71, v72, v13
	v_mov_b32_e32 v13, v125
	ds_bpermute_b32 v252, v250, v70
	ds_bpermute_b32 v253, v250, v71
	s_waitcnt lgkmcnt(2)
	global_store_dwordx2 v[244:245], v[254:255], off offset:64
	s_nop 0
	v_mul_f32_e32 v66, v66, v13
	v_mul_f32_e32 v67, v67, v13
	v_mul_f32_e32 v68, v68, v13
	v_mul_f32_e32 v13, v69, v13
	s_nop 0
	v_cvt_pk_bf16_f32 v66, v66, v67
	v_cvt_pk_bf16_f32 v67, v68, v13
	ds_bpermute_b32 v254, v250, v66
	ds_bpermute_b32 v255, v250, v67
	s_waitcnt lgkmcnt(2)
	global_store_dwordx2 v[246:247], v[252:253], off offset:64
	s_nop 0
	v_mul_f32_e32 v13, v62, v126
	v_mul_f32_e32 v62, v63, v126
	v_mul_f32_e32 v63, v64, v126
	v_mul_f32_e32 v64, v65, v126
	s_nop 0
	v_cvt_pk_bf16_f32 v62, v13, v62
	v_cvt_pk_bf16_f32 v63, v63, v64
	ds_bpermute_b32 v252, v250, v62
	ds_bpermute_b32 v253, v250, v63
	s_waitcnt lgkmcnt(2)
	global_store_dwordx2 v[248:249], v[254:255], off offset:64
	s_nop 0
	v_mul_f32_e32 v13, v58, v127
	v_mul_f32_e32 v58, v59, v127
	v_mul_f32_e32 v59, v60, v127
	v_mul_f32_e32 v60, v61, v127
	s_nop 0
	v_cvt_pk_bf16_f32 v58, v13, v58
	v_cvt_pk_bf16_f32 v59, v59, v60
	ds_bpermute_b32 v254, v250, v58
	ds_bpermute_b32 v255, v250, v59
	s_waitcnt lgkmcnt(2)
	global_store_dwordx2 v[242:243], v[252:253], off offset:96
	s_nop 0
	v_mul_f32_e32 v13, v46, v124
	v_mul_f32_e32 v46, v47, v124
	v_mul_f32_e32 v47, v48, v124
	v_mul_f32_e32 v48, v49, v124
	s_nop 0
	v_cvt_pk_bf16_f32 v46, v13, v46
	v_cvt_pk_bf16_f32 v47, v47, v48
	ds_bpermute_b32 v252, v250, v46
	ds_bpermute_b32 v253, v250, v47
	s_waitcnt lgkmcnt(2)
	global_store_dwordx2 v[244:245], v[254:255], off offset:96
	s_nop 0
	v_mul_f32_e32 v13, v26, v125
	v_mul_f32_e32 v26, v27, v125
	v_mul_f32_e32 v27, v28, v125
	v_mul_f32_e32 v28, v29, v125
	s_nop 0
	v_cvt_pk_bf16_f32 v26, v13, v26
	v_cvt_pk_bf16_f32 v27, v27, v28
	ds_bpermute_b32 v254, v250, v26
	ds_bpermute_b32 v255, v250, v27
	s_waitcnt lgkmcnt(2)
	global_store_dwordx2 v[246:247], v[252:253], off offset:96
	s_waitcnt lgkmcnt(0)
	global_store_dwordx2 v[248:249], v[254:255], off offset:96

; template <int EPI, int TI>
; __device__ __forceinline__ void gemm_epilogue(const WS& ws, const f32x4 (&acc)[4][TI], const float (&rs)[TI], int tok0, int n0,
;                                               int wm, int wn, int lr, int lq, bool dry) {
;     ...
;   } else if (EPI == EPI_KV) {
;     const int hd = nw >> 7;
;     const bool isv = (nw & 127) >= 64;
;     if (!isv) {
; #pragma unroll
;       for (int ni = 0; ni < 4; ++ni)
; #pragma unroll
;         for (int ti = 0; ti < TI; ++ti) {
;           const f32x4 v = scale4(acc[ni][ti], rs[ti]);
;           u32x2 pk; pk.x = cvt_pk_bf16(v[0], v[1]); pk.y = cvt_pk_bf16(v[2], v[3]);
;           if (okr(ti)) *(u32x2*)(ws.KN + (size_t)tokr(ti) * 1024 + hd * 64 + ni * 16 + 4 * lq) = pk;
;         }
.LBB0_772:
	v_mbcnt_lo_u32_b32 v250, -1, 0
	v_mbcnt_hi_u32_b32 v250, -1, v250
	v_and_b32_e32 v251, 3, v250
	v_lshrrev_b32_e32 v250, 2, v250
	v_lshl_add_u32 v250, v251, 4, v250
	v_lshlrev_b32_e32 v250, 2, v250
	s_andn2_saveexec_b64 s[4:5], s[4:5]
	s_cbranch_execz .LBB0_774
	v_lshlrev_b32_e32 v132, 6, v13
	s_waitcnt lgkmcnt(1)
	v_mov_b32_e32 v13, v128
	v_ashrrev_i32_e32 v131, 31, v130
	v_mul_f32_e32 v110, v110, v13
	v_mul_f32_e32 v111, v111, v13
	v_mul_f32_e32 v112, v112, v13
	v_mul_f32_e32 v13, v113, v13
	v_ashrrev_i32_e32 v133, 31, v132
	v_cvt_pk_bf16_f32 v110, v110, v111
	v_cvt_pk_bf16_f32 v111, v112, v13
	v_lshlrev_b64 v[112:113], 11, v[130:131]
	v_lshl_add_u64 v[112:113], s[46:47], 0, v[112:113]
	v_lshl_add_u64 v[112:113], v[132:133], 1, v[112:113]
	v_mov_b32_e32 v121, v12
	v_lshl_add_u64 v[112:113], v[112:113], 0, v[120:121]
	v_mov_b32_e32 v13, v129
	ds_bpermute_b32 v242, v250, v112
	ds_bpermute_b32 v243, v250, v113
	ds_bpermute_b32 v252, v250, v110
	ds_bpermute_b32 v253, v250, v111
	s_mov_b32 s3, 0x8000
	v_mul_f32_e32 v102, v102, v13
	v_mul_f32_e32 v103, v103, v13
	v_mul_f32_e32 v104, v104, v13
	v_mul_f32_e32 v13, v105, v13
	v_add_co_u32_e32 v110, vcc, s3, v112
	v_cvt_pk_bf16_f32 v102, v102, v103
	v_cvt_pk_bf16_f32 v103, v104, v13
	v_addc_co_u32_e32 v111, vcc, 0, v113, vcc
	s_waitcnt lgkmcnt(0)
	v_mov_b32_e32 v13, v126
	ds_bpermute_b32 v244, v250, v110
	ds_bpermute_b32 v245, v250, v111
	ds_bpermute_b32 v254, v250, v102
	ds_bpermute_b32 v255, v250, v103
	s_waitcnt lgkmcnt(4)
	global_store_dwordx2 v[242:243], v[252:253], off
	v_add_co_u32_e32 v102, vcc, s82, v112
	v_mul_f32_e32 v86, v86, v13
	v_mul_f32_e32 v87, v87, v13
	v_mul_f32_e32 v88, v88, v13
	v_mul_f32_e32 v13, v89, v13
	v_addc_co_u32_e32 v103, vcc, 0, v113, vcc
	v_cvt_pk_bf16_f32 v86, v86, v87
	v_cvt_pk_bf16_f32 v87, v88, v13
	v_mov_b32_e32 v13, v127
	ds_bpermute_b32 v246, v250, v102
	ds_bpermute_b32 v247, v250, v103
	ds_bpermute_b32 v252, v250, v86
	ds_bpermute_b32 v253, v250, v87
	s_waitcnt lgkmcnt(4)
	global_store_dwordx2 v[244:245], v[254:255], off
	s_mov_b32 s3, 0x18000
	v_mul_f32_e32 v70, v70, v13
	v_mul_f32_e32 v71, v71, v13
	v_mul_f32_e32 v72, v72, v13
	v_mul_f32_e32 v13, v73, v13
	v_add_co_u32_e32 v86, vcc, s3, v112
	v_cvt_pk_bf16_f32 v70, v70, v71
	v_cvt_pk_bf16_f32 v71, v72, v13
	v_addc_co_u32_e32 v87, vcc, 0, v113, vcc
	v_mov_b32_e32 v13, v128
	ds_bpermute_b32 v248, v250, v86
	ds_bpermute_b32 v249, v250, v87
	ds_bpermute_b32 v254, v250, v70
	ds_bpermute_b32 v255, v250, v71
	s_waitcnt lgkmcnt(4)
	global_store_dwordx2 v[246:247], v[252:253], off
	s_mov_b64 s[10:11], 0x8000
	v_mul_f32_e32 v70, v106, v13
	v_mul_f32_e32 v71, v107, v13
	v_mul_f32_e32 v86, v108, v13
	v_mul_f32_e32 v13, v109, v13
	v_lshl_add_u64 v[104:105], v[112:113], 0, s[10:11]
	v_cvt_pk_bf16_f32 v70, v70, v71
	v_cvt_pk_bf16_f32 v71, v86, v13
	v_mov_b32_e32 v13, v129
	ds_bpermute_b32 v252, v250, v70
	ds_bpermute_b32 v253, v250, v71
	s_waitcnt lgkmcnt(2)
	global_store_dwordx2 v[248:249], v[254:255], off
	s_mov_b64 s[10:11], 0x10000
	v_mul_f32_e32 v70, v94, v13
	v_mul_f32_e32 v71, v95, v13
	v_mul_f32_e32 v86, v96, v13
	v_mul_f32_e32 v13, v97, v13
	v_lshl_add_u64 v[88:89], v[112:113], 0, s[10:11]
	v_cvt_pk_bf16_f32 v70, v70, v71
	v_cvt_pk_bf16_f32 v71, v86, v13
	v_mov_b32_e32 v13, v126
	ds_bpermute_b32 v248, v250, v104
	ds_bpermute_b32 v249, v250, v105
	ds_bpermute_b32 v254, v250, v70
	ds_bpermute_b32 v255, v250, v71
	s_waitcnt lgkmcnt(4)
	global_store_dwordx2 v[242:243], v[252:253], off offset:32
	s_mov_b64 s[10:11], 0x18000
	v_mul_f32_e32 v70, v78, v13
	v_mul_f32_e32 v71, v79, v13
	v_mul_f32_e32 v78, v80, v13
	v_mul_f32_e32 v13, v81, v13
	v_lshl_add_u64 v[72:73], v[112:113], 0, s[10:11]
	v_cvt_pk_bf16_f32 v70, v70, v71
	v_cvt_pk_bf16_f32 v71, v78, v13
	v_mov_b32_e32 v13, v127
	ds_bpermute_b32 v242, v250, v88
	ds_bpermute_b32 v243, v250, v89
	ds_bpermute_b32 v252, v250, v70
	ds_bpermute_b32 v253, v250, v71
	s_waitcnt lgkmcnt(4)
; template <int EPI, int TI>
; __device__ __forceinline__ void gemm_epilogue(const WS& ws, const f32x4 (&acc)[4][TI], const float (&rs)[TI], int tok0, int n0,
;                                               int wm, int wn, int lr, int lq, bool dry) {
;     ...
;   } else if (EPI == EPI_KV) {
;     const int hd = nw >> 7;
;     const bool isv = (nw & 127) >= 64;
;     if (!isv) {
; #pragma unroll
;       for (int ni = 0; ni < 4; ++ni)
; #pragma unroll
;         for (int ti = 0; ti < TI; ++ti) {
;           const f32x4 v = scale4(acc[ni][ti], rs[ti]);
;           u32x2 pk; pk.x = cvt_pk_bf16(v[0], v[1]); pk.y = cvt_pk_bf16(v[2], v[3]);
;           if (okr(ti)) *(u32x2*)(ws.KN + (size_t)tokr(ti) * 1024 + hd * 64 + ni * 16 + 4 * lq) = pk;
;         }
	global_store_dwordx2 v[248:249], v[254:255], off offset:32
	s_nop 0
	v_mul_f32_e32 v62, v62, v13
	v_mul_f32_e32 v63, v63, v13
	v_mul_f32_e32 v64, v64, v13
	v_mul_f32_e32 v13, v65, v13
	s_nop 0
	v_cvt_pk_bf16_f32 v62, v62, v63
	v_cvt_pk_bf16_f32 v63, v64, v13
	v_mov_b32_e32 v13, v128
	ds_bpermute_b32 v244, v250, v72
	ds_bpermute_b32 v245, v250, v73
	ds_bpermute_b32 v254, v250, v62
	ds_bpermute_b32 v255, v250, v63
	s_waitcnt lgkmcnt(4)
	global_store_dwordx2 v[242:243], v[252:253], off offset:32
	s_nop 0
	v_mul_f32_e32 v62, v98, v13
	v_mul_f32_e32 v63, v99, v13
	v_mul_f32_e32 v64, v100, v13
	v_mul_f32_e32 v13, v101, v13
	s_nop 0
	v_cvt_pk_bf16_f32 v62, v62, v63
	v_cvt_pk_bf16_f32 v63, v64, v13
	v_mov_b32_e32 v13, v129
	ds_bpermute_b32 v246, v250, v112
	ds_bpermute_b32 v247, v250, v113
	ds_bpermute_b32 v252, v250, v62
	ds_bpermute_b32 v253, v250, v63
	s_waitcnt lgkmcnt(4)
	global_store_dwordx2 v[244:245], v[254:255], off offset:32
	s_nop 0
	v_mul_f32_e32 v62, v82, v13
	v_mul_f32_e32 v63, v83, v13
	v_mul_f32_e32 v64, v84, v13
	v_mul_f32_e32 v13, v85, v13
	s_nop 0
	v_cvt_pk_bf16_f32 v62, v62, v63
	v_cvt_pk_bf16_f32 v63, v64, v13
	v_mov_b32_e32 v13, v126
	ds_bpermute_b32 v254, v250, v62
	ds_bpermute_b32 v255, v250, v63
	s_waitcnt lgkmcnt(2)
	global_store_dwordx2 v[246:247], v[252:253], off offset:64
	s_nop 0
	v_mul_f32_e32 v62, v66, v13
	v_mul_f32_e32 v63, v67, v13
	v_mul_f32_e32 v64, v68, v13
	v_mul_f32_e32 v13, v69, v13
	s_nop 0
	v_cvt_pk_bf16_f32 v62, v62, v63
	v_cvt_pk_bf16_f32 v63, v64, v13
	v_mov_b32_e32 v13, v127
	ds_bpermute_b32 v252, v250, v62
	ds_bpermute_b32 v253, v250, v63
	s_waitcnt lgkmcnt(2)
	global_store_dwordx2 v[248:249], v[254:255], off offset:64
	s_nop 0
	v_mul_f32_e32 v54, v54, v13
	v_mul_f32_e32 v55, v55, v13
	v_mul_f32_e32 v56, v56, v13
	v_mul_f32_e32 v13, v57, v13
	s_nop 0
	v_cvt_pk_bf16_f32 v54, v54, v55
	v_cvt_pk_bf16_f32 v55, v56, v13
	ds_bpermute_b32 v254, v250, v54
	ds_bpermute_b32 v255, v250, v55
	s_waitcnt lgkmcnt(2)
	global_store_dwordx2 v[242:243], v[252:253], off offset:64
	s_nop 0
	v_mul_f32_e32 v13, v90, v128
	v_mul_f32_e32 v54, v91, v128
	v_mul_f32_e32 v55, v92, v128
	v_mul_f32_e32 v56, v93, v128
	s_nop 0
	v_cvt_pk_bf16_f32 v54, v13, v54
	v_cvt_pk_bf16_f32 v55, v55, v56
	ds_bpermute_b32 v252, v250, v54
	ds_bpermute_b32 v253, v250, v55
	s_waitcnt lgkmcnt(2)
	global_store_dwordx2 v[244:245], v[254:255], off offset:64
	s_nop 0
	v_mul_f32_e32 v13, v74, v129
	v_mul_f32_e32 v54, v75, v129
	v_mul_f32_e32 v55, v76, v129
	v_mul_f32_e32 v56, v77, v129
	s_nop 0
	v_cvt_pk_bf16_f32 v54, v13, v54
	v_cvt_pk_bf16_f32 v55, v55, v56
	ds_bpermute_b32 v254, v250, v54
	ds_bpermute_b32 v255, v250, v55
	s_waitcnt lgkmcnt(2)
	global_store_dwordx2 v[246:247], v[252:253], off offset:96
	s_nop 0
	v_mul_f32_e32 v13, v58, v126
	v_mul_f32_e32 v54, v59, v126
	v_mul_f32_e32 v55, v60, v126
	v_mul_f32_e32 v56, v61, v126
	s_nop 0
	v_cvt_pk_bf16_f32 v54, v13, v54
	v_cvt_pk_bf16_f32 v55, v55, v56
	ds_bpermute_b32 v252, v250, v54
	ds_bpermute_b32 v253, v250, v55
	s_waitcnt lgkmcnt(2)
	global_store_dwordx2 v[248:249], v[254:255], off offset:96
	s_nop 0
	v_mul_f32_e32 v13, v50, v127
	v_mul_f32_e32 v50, v51, v127
	v_mul_f32_e32 v51, v52, v127
	v_mul_f32_e32 v52, v53, v127
	s_nop 0
	v_cvt_pk_bf16_f32 v50, v13, v50
	v_cvt_pk_bf16_f32 v51, v51, v52
	ds_bpermute_b32 v254, v250, v50
	ds_bpermute_b32 v255, v250, v51
	s_waitcnt lgkmcnt(2)
	global_store_dwordx2 v[242:243], v[252:253], off offset:96
	s_waitcnt lgkmcnt(0)
	global_store_dwordx2 v[244:245], v[254:255], off offset:96

; template <int EPI, int TI>
; __device__ __forceinline__ void gemm_epilogue(const WS& ws, const f32x4 (&acc)[4][TI], const float (&rs)[TI], int tok0, int n0,
;                                               int wm, int wn, int lr, int lq, bool dry) {
;     ...
;   if (EPI == EPI_E1) {
;     bf16_t* dst; int ld, c;
;     if (n0 < 1024) { dst = ws.XA; ld = 1024; c = n0; }
;     else if (n0 < 2048) { dst = ws.GA; ld = 1024; c = n0 - 1024; }
;     else if (n0 < 2560) { dst = ws.Q; ld = 512; c = n0 - 2048; }
;     else if (n0 < 3072) { dst = ws.K; ld = 512; c = n0 - 2560; }
;     else if (n0 < 4096) { dst = ws.V; ld = 1024; c = n0 - 3072; }
;     else if (n0 < 5120) { dst = ws.GB; ld = 1024; c = n0 - 4096; }
;     else { dst = ws.AD; ld = 16; c = 0; }
;     const bool isad = n0 >= 5120;
; #pragma unroll
;     for (int ni = 0; ni < 4; ++ni) {
;       if (isad && (wm != 0 || ni != 0)) continue;
; #pragma unroll
;       for (int ti = 0; ti < TI; ++ti) {
;         const f32x4 v = scale4(acc[ni][ti], rs[ti]);
;         u32x2 pk; pk.x = cvt_pk_bf16(v[0], v[1]); pk.y = cvt_pk_bf16(v[2], v[3]);
;         if (okr(ti)) *(u32x2*)(dst + (size_t)tokr(ti) * ld + c + wm * 64 + ni * 16 + 4 * lq) = pk;
;       }
;     }
; template <int EPI>
; __device__ __forceinline__ void gemm_wide(const WS& ws, const bf16_t* A, int lda, const bf16_t* __restrict__ W, int K, float invK,
;                                           int ntn, int ntiles, int bid) {
;     ...
;       for (int ti = 0; ti < 4; ++ti) rs[ti] = rsl[wn * 64 + ti * 16 + lr];
;       int mt, nt; tile_of(c_id, ntn, mt, nt);
;       const int tokb = mt * 256 + hh * 128;
;       if (tokb < M_) {
;         gemm_epilogue<EPI, 4>(ws, accA, rs, tokb, nt * 256, wm, wn, lr, lq, false);
;         if (nt * 256 + 128 < 5248) gemm_epilogue<EPI, 4>(ws, accB, rs, tokb, nt * 256 + 128, wm, wn, lr, lq, false);
.LBB0_1067:
	v_mbcnt_lo_u32_b32 v250, -1, 0
	v_mbcnt_hi_u32_b32 v250, -1, v250
	v_and_b32_e32 v251, 3, v250
	v_lshrrev_b32_e32 v250, 2, v250
	v_lshl_add_u32 v250, v251, 4, v250
	v_lshlrev_b32_e32 v250, 2, v250
	s_cmp_lt_i32 s7, 20
	s_cselect_b64 s[60:61], -1, 0
	s_ashr_i32 s7, s6, 31
	s_lshl_b64 s[6:7], s[6:7], 1
	s_add_u32 s6, s12, s6
	v_add_u32_e32 v215, s9, v209
	s_addc_u32 s7, s13, s7
	v_lshl_add_u64 v[184:185], v[172:173], 1, s[6:7]
	v_lshlrev_b32_e32 v182, 1, v174
	v_mov_b32_e32 v183, v12
	v_ashrrev_i32_e32 v217, 31, v215
	v_add_u32_e32 v214, 16, v215
	v_add_u32_e32 v212, 32, v215
	v_add_u32_e32 v13, 48, v215
	v_lshl_add_u64 v[184:185], v[184:185], 0, v[182:183]
	s_or_b64 s[10:11], s[38:39], s[60:61]
	v_mul_lo_u32 v220, s5, v215
	v_mul_lo_u32 v221, s4, v217
	v_ashrrev_i32_e32 v216, 31, v214
	v_mul_lo_u32 v219, s5, v214
	v_ashrrev_i32_e32 v213, 31, v212
	v_mul_lo_u32 v218, s5, v212
	v_ashrrev_i32_e32 v169, 31, v13
	v_mul_lo_u32 v183, s5, v13
	s_and_saveexec_b64 s[6:7], s[10:11]
	s_cbranch_execz .LBB0_1070
	s_waitcnt lgkmcnt(1)
	v_mov_b32_e32 v222, v180
	s_nop 0
	v_mul_f32_e32 v158, v158, v222
	v_mul_f32_e32 v159, v159, v222
	v_mul_f32_e32 v160, v160, v222
	v_mul_f32_e32 v161, v161, v222
	s_nop 0
	v_cvt_pk_bf16_f32 v158, v158, v159
	v_cvt_pk_bf16_f32 v159, v160, v161
	v_mad_u64_u32 v[160:161], s[10:11], s4, v215, 0
	v_add3_u32 v161, v161, v221, v220
	v_lshl_add_u64 v[160:161], v[160:161], 1, v[184:185]
	ds_bpermute_b32 v242, v250, v160
	ds_bpermute_b32 v243, v250, v161
	ds_bpermute_b32 v252, v250, v158
	ds_bpermute_b32 v253, v250, v159
	v_mov_b32_e32 v158, v181
	s_nop 0
	v_mul_f32_e32 v154, v154, v158
	v_mul_f32_e32 v155, v155, v158
	v_mul_f32_e32 v156, v156, v158
	v_mul_f32_e32 v157, v157, v158
	v_mul_lo_u32 v158, s4, v216
	v_cvt_pk_bf16_f32 v154, v154, v155
	v_cvt_pk_bf16_f32 v155, v156, v157
	v_mad_u64_u32 v[156:157], s[10:11], s4, v214, 0
	v_add3_u32 v157, v157, v158, v219
	v_lshl_add_u64 v[156:157], v[156:157], 1, v[184:185]
	ds_bpermute_b32 v244, v250, v156
	ds_bpermute_b32 v245, v250, v157
	ds_bpermute_b32 v254, v250, v154
	ds_bpermute_b32 v255, v250, v155
	s_waitcnt lgkmcnt(4)
	global_store_dwordx2 v[242:243], v[252:253], off
	s_waitcnt lgkmcnt(0)
	v_mov_b32_e32 v154, v178
	s_nop 0
	v_mul_f32_e32 v150, v150, v154
	v_mul_f32_e32 v151, v151, v154
	v_mul_f32_e32 v152, v152, v154
	v_mul_f32_e32 v153, v153, v154
	v_mul_lo_u32 v154, s4, v213
	v_cvt_pk_bf16_f32 v150, v150, v151
	v_cvt_pk_bf16_f32 v151, v152, v153
	v_mad_u64_u32 v[152:153], s[10:11], s4, v212, 0
	v_add3_u32 v153, v153, v154, v218
	v_lshl_add_u64 v[152:153], v[152:153], 1, v[184:185]
	ds_bpermute_b32 v246, v250, v152
	ds_bpermute_b32 v247, v250, v153
	ds_bpermute_b32 v252, v250, v150
	ds_bpermute_b32 v253, v250, v151
	s_waitcnt lgkmcnt(4)
	global_store_dwordx2 v[244:245], v[254:255], off
	v_mov_b32_e32 v150, v179
	s_nop 0
	v_mul_f32_e32 v146, v146, v150
	v_mul_f32_e32 v147, v147, v150
	v_mul_f32_e32 v148, v148, v150
	v_mul_f32_e32 v149, v149, v150
	v_mul_lo_u32 v150, s4, v169
	v_cvt_pk_bf16_f32 v146, v146, v147
	v_cvt_pk_bf16_f32 v147, v148, v149
	v_mad_u64_u32 v[148:149], s[10:11], s4, v13, 0
	v_add3_u32 v149, v149, v150, v183
	v_lshl_add_u64 v[148:149], v[148:149], 1, v[184:185]
	ds_bpermute_b32 v248, v250, v148
	ds_bpermute_b32 v249, v250, v149
	ds_bpermute_b32 v254, v250, v146
	ds_bpermute_b32 v255, v250, v147
	s_waitcnt lgkmcnt(4)
	global_store_dwordx2 v[246:247], v[252:253], off
	s_waitcnt lgkmcnt(0)
	global_store_dwordx2 v[248:249], v[254:255], off
	s_or_b64 exec, exec, s[6:7]
	s_andn2_b64 vcc, exec, s[60:61]
	s_cbranch_vccz .LBB0_1071

; template <int EPI, int TI>
; __device__ __forceinline__ void gemm_epilogue(const WS& ws, const f32x4 (&acc)[4][TI], const float (&rs)[TI], int tok0, int n0,
;                                               int wm, int wn, int lr, int lq, bool dry) {
;     ...
;   if (EPI == EPI_E1) {
;     bf16_t* dst; int ld, c;
;     if (n0 < 1024) { dst = ws.XA; ld = 1024; c = n0; }
;     else if (n0 < 2048) { dst = ws.GA; ld = 1024; c = n0 - 1024; }
;     else if (n0 < 2560) { dst = ws.Q; ld = 512; c = n0 - 2048; }
;     else if (n0 < 3072) { dst = ws.K; ld = 512; c = n0 - 2560; }
;     else if (n0 < 4096) { dst = ws.V; ld = 1024; c = n0 - 3072; }
;     else if (n0 < 5120) { dst = ws.GB; ld = 1024; c = n0 - 4096; }
;     else { dst = ws.AD; ld = 16; c = 0; }
;     const bool isad = n0 >= 5120;
; #pragma unroll
;     for (int ni = 0; ni < 4; ++ni) {
;       if (isad && (wm != 0 || ni != 0)) continue;
; #pragma unroll
;       for (int ti = 0; ti < TI; ++ti) {
;         const f32x4 v = scale4(acc[ni][ti], rs[ti]);
;         u32x2 pk; pk.x = cvt_pk_bf16(v[0], v[1]); pk.y = cvt_pk_bf16(v[2], v[3]);
;         if (okr(ti)) *(u32x2*)(dst + (size_t)tokr(ti) * ld + c + wm * 64 + ni * 16 + 4 * lq) = pk;
;       }
;     }
; template <int EPI>
; __device__ __forceinline__ void gemm_wide(const WS& ws, const bf16_t* A, int lda, const bf16_t* __restrict__ W, int K, float invK,
;                                           int ntn, int ntiles, int bid) {
;     ...
;       for (int ti = 0; ti < 4; ++ti) rs[ti] = rsl[wn * 64 + ti * 16 + lr];
;       int mt, nt; tile_of(c_id, ntn, mt, nt);
;       const int tokb = mt * 256 + hh * 128;
;       if (tokb < M_) {
;         gemm_epilogue<EPI, 4>(ws, accA, rs, tokb, nt * 256, wm, wn, lr, lq, false);
;         if (nt * 256 + 128 < 5248) gemm_epilogue<EPI, 4>(ws, accB, rs, tokb, nt * 256 + 128, wm, wn, lr, lq, false);
.LBB0_1071:
	s_waitcnt lgkmcnt(1)
	v_mov_b32_e32 v146, v180
	s_nop 0
	v_mul_f32_e32 v142, v142, v146
	v_mul_f32_e32 v143, v143, v146
	v_mul_f32_e32 v144, v144, v146
	v_mul_f32_e32 v145, v145, v146
	s_nop 0
	v_cvt_pk_bf16_f32 v142, v142, v143
	v_cvt_pk_bf16_f32 v143, v144, v145
	v_mad_u64_u32 v[144:145], s[6:7], s4, v215, 0
	v_add3_u32 v145, v145, v221, v220
	v_lshl_add_u64 v[144:145], v[144:145], 1, v[184:185]
	ds_bpermute_b32 v242, v250, v144
	ds_bpermute_b32 v243, v250, v145
	ds_bpermute_b32 v252, v250, v142
	ds_bpermute_b32 v253, v250, v143
	v_mov_b32_e32 v142, v181
	s_nop 0
	v_mul_f32_e32 v138, v138, v142
	v_mul_f32_e32 v139, v139, v142
	v_mul_f32_e32 v140, v140, v142
	v_mul_f32_e32 v141, v141, v142
	v_mul_lo_u32 v142, s4, v216
	v_cvt_pk_bf16_f32 v138, v138, v139
	v_cvt_pk_bf16_f32 v139, v140, v141
	v_mad_u64_u32 v[140:141], s[6:7], s4, v214, 0
	v_add3_u32 v141, v141, v142, v219
	v_lshl_add_u64 v[140:141], v[140:141], 1, v[184:185]
	ds_bpermute_b32 v244, v250, v140
	ds_bpermute_b32 v245, v250, v141
	ds_bpermute_b32 v254, v250, v138
	ds_bpermute_b32 v255, v250, v139
	s_waitcnt lgkmcnt(4)
	global_store_dwordx2 v[242:243], v[252:253], off offset:32
	s_waitcnt lgkmcnt(0)
	v_mov_b32_e32 v138, v178
	s_nop 0
	v_mul_f32_e32 v130, v130, v138
	v_mul_f32_e32 v131, v131, v138
	v_mul_f32_e32 v132, v132, v138
	v_mul_f32_e32 v133, v133, v138
	v_mul_lo_u32 v138, s4, v213
	v_cvt_pk_bf16_f32 v130, v130, v131
	v_cvt_pk_bf16_f32 v131, v132, v133
	v_mad_u64_u32 v[132:133], s[6:7], s4, v212, 0
	v_add3_u32 v133, v133, v138, v218
	v_lshl_add_u64 v[132:133], v[132:133], 1, v[184:185]
	ds_bpermute_b32 v246, v250, v132
	ds_bpermute_b32 v247, v250, v133
	ds_bpermute_b32 v252, v250, v130
	ds_bpermute_b32 v253, v250, v131
	s_waitcnt lgkmcnt(4)
	global_store_dwordx2 v[244:245], v[254:255], off offset:32
	v_mov_b32_e32 v130, v179
	s_nop 0
	v_mul_f32_e32 v114, v114, v130
	v_mul_f32_e32 v115, v115, v130
	v_mul_f32_e32 v116, v116, v130
	v_mul_f32_e32 v117, v117, v130
	v_mul_lo_u32 v130, s4, v169
	v_cvt_pk_bf16_f32 v114, v114, v115
	v_cvt_pk_bf16_f32 v115, v116, v117
	v_mad_u64_u32 v[116:117], s[4:5], s4, v13, 0
	v_add3_u32 v117, v117, v130, v183
	v_lshl_add_u64 v[116:117], v[116:117], 1, v[184:185]
	ds_bpermute_b32 v248, v250, v116
	ds_bpermute_b32 v249, v250, v117
	ds_bpermute_b32 v254, v250, v114
	ds_bpermute_b32 v255, v250, v115
	s_waitcnt lgkmcnt(4)
	global_store_dwordx2 v[246:247], v[252:253], off offset:32
	v_mov_b32_e32 v114, v180
	s_nop 0
	v_mul_f32_e32 v94, v94, v114
	v_mul_f32_e32 v95, v95, v114
	v_mul_f32_e32 v96, v96, v114
	v_mul_f32_e32 v97, v97, v114
	s_nop 0
	v_cvt_pk_bf16_f32 v94, v94, v95
	v_cvt_pk_bf16_f32 v95, v96, v97
	ds_bpermute_b32 v252, v250, v94
	ds_bpermute_b32 v253, v250, v95
	s_waitcnt lgkmcnt(2)
	global_store_dwordx2 v[248:249], v[254:255], off offset:32
	v_mov_b32_e32 v94, v181
	s_nop 0
	v_mul_f32_e32 v90, v90, v94
	v_mul_f32_e32 v91, v91, v94
	v_mul_f32_e32 v92, v92, v94
	v_mul_f32_e32 v93, v93, v94
	s_nop 0
	v_cvt_pk_bf16_f32 v90, v90, v91
	v_cvt_pk_bf16_f32 v91, v92, v93
	ds_bpermute_b32 v254, v250, v90
	ds_bpermute_b32 v255, v250, v91
	s_waitcnt lgkmcnt(2)
	global_store_dwordx2 v[242:243], v[252:253], off offset:64
	v_mov_b32_e32 v90, v178
	s_nop 0
	v_mul_f32_e32 v86, v86, v90
	v_mul_f32_e32 v87, v87, v90
	v_mul_f32_e32 v88, v88, v90
	v_mul_f32_e32 v89, v89, v90
	s_nop 0
	v_cvt_pk_bf16_f32 v86, v86, v87
	v_cvt_pk_bf16_f32 v87, v88, v89
	ds_bpermute_b32 v252, v250, v86
	ds_bpermute_b32 v253, v250, v87
	s_waitcnt lgkmcnt(2)
	global_store_dwordx2 v[244:245], v[254:255], off offset:64
	v_mov_b32_e32 v86, v179
	s_nop 0
	v_mul_f32_e32 v82, v82, v86
	v_mul_f32_e32 v83, v83, v86
	v_mul_f32_e32 v84, v84, v86
	v_mul_f32_e32 v85, v85, v86
	s_nop 0
	v_cvt_pk_bf16_f32 v82, v82, v83
	v_cvt_pk_bf16_f32 v83, v84, v85
	ds_bpermute_b32 v254, v250, v82
	ds_bpermute_b32 v255, v250, v83
	s_waitcnt lgkmcnt(2)
	global_store_dwordx2 v[246:247], v[252:253], off offset:64
	v_mov_b32_e32 v82, v180
	s_nop 0
	v_mul_f32_e32 v78, v78, v82
	v_mul_f32_e32 v79, v79, v82
	v_mul_f32_e32 v80, v80, v82
	v_mul_f32_e32 v81, v81, v82
	s_nop 0
	v_cvt_pk_bf16_f32 v78, v78, v79
	v_cvt_pk_bf16_f32 v79, v80, v81
	ds_bpermute_b32 v252, v250, v78
	ds_bpermute_b32 v253, v250, v79
	s_waitcnt lgkmcnt(2)
	global_store_dwordx2 v[248:249], v[254:255], off offset:64
	v_mov_b32_e32 v78, v181
	s_nop 0
	v_mul_f32_e32 v74, v74, v78
	v_mul_f32_e32 v75, v75, v78
	v_mul_f32_e32 v76, v76, v78
	v_mul_f32_e32 v77, v77, v78
	s_nop 0
	v_cvt_pk_bf16_f32 v74, v74, v75
	v_cvt_pk_bf16_f32 v75, v76, v77
	ds_bpermute_b32 v254, v250, v74
	ds_bpermute_b32 v255, v250, v75
	s_waitcnt lgkmcnt(2)
	global_store_dwordx2 v[242:243], v[252:253], off offset:96
	v_mov_b32_e32 v74, v178
	s_nop 0
	v_mul_f32_e32 v70, v70, v74
	v_mul_f32_e32 v71, v71, v74
	v_mul_f32_e32 v72, v72, v74
	v_mul_f32_e32 v73, v73, v74
	s_nop 0
	v_cvt_pk_bf16_f32 v70, v70, v71
	v_cvt_pk_bf16_f32 v71, v72, v73
	ds_bpermute_b32 v252, v250, v70
	ds_bpermute_b32 v253, v250, v71
	s_waitcnt lgkmcnt(2)
	global_store_dwordx2 v[244:245], v[254:255], off offset:96
	v_mov_b32_e32 v70, v179
	s_nop 0
	v_mul_f32_e32 v66, v66, v70
	v_mul_f32_e32 v67, v67, v70
	v_mul_f32_e32 v68, v68, v70
	v_mul_f32_e32 v69, v69, v70
	s_nop 0
	v_cvt_pk_bf16_f32 v66, v66, v67
	v_cvt_pk_bf16_f32 v67, v68, v69
	ds_bpermute_b32 v254, v250, v66
	ds_bpermute_b32 v255, v250, v67
	s_waitcnt lgkmcnt(2)
	global_store_dwordx2 v[246:247], v[252:253], off offset:96
	s_or_b32 s7, s8, 0x80
	s_cmpk_gt_i32 s7, 0x147f
	s_waitcnt lgkmcnt(0)
	global_store_dwordx2 v[248:249], v[254:255], off offset:96
	s_cbranch_scc1 .LBB0_1093

; template <int EPI, int TI>
; __device__ __forceinline__ void gemm_epilogue(const WS& ws, const f32x4 (&acc)[4][TI], const float (&rs)[TI], int tok0, int n0,
;                                               int wm, int wn, int lr, int lq, bool dry) {
;     ...
;   if (EPI == EPI_E1) {
;     bf16_t* dst; int ld, c;
;     if (n0 < 1024) { dst = ws.XA; ld = 1024; c = n0; }
;     else if (n0 < 2048) { dst = ws.GA; ld = 1024; c = n0 - 1024; }
;     else if (n0 < 2560) { dst = ws.Q; ld = 512; c = n0 - 2048; }
;     else if (n0 < 3072) { dst = ws.K; ld = 512; c = n0 - 2560; }
;     else if (n0 < 4096) { dst = ws.V; ld = 1024; c = n0 - 3072; }
;     else if (n0 < 5120) { dst = ws.GB; ld = 1024; c = n0 - 4096; }
;     else { dst = ws.AD; ld = 16; c = 0; }
;     const bool isad = n0 >= 5120;
; #pragma unroll
;     for (int ni = 0; ni < 4; ++ni) {
;       if (isad && (wm != 0 || ni != 0)) continue;
; #pragma unroll
;       for (int ti = 0; ti < TI; ++ti) {
;         const f32x4 v = scale4(acc[ni][ti], rs[ti]);
;         u32x2 pk; pk.x = cvt_pk_bf16(v[0], v[1]); pk.y = cvt_pk_bf16(v[2], v[3]);
;         if (okr(ti)) *(u32x2*)(dst + (size_t)tokr(ti) * ld + c + wm * 64 + ni * 16 + 4 * lq) = pk;
;       }
;     }
; template <int EPI>
; __device__ __forceinline__ void gemm_wide(const WS& ws, const bf16_t* A, int lda, const bf16_t* __restrict__ W, int K, float invK,
;                                           int ntn, int ntiles, int bid) {
;     ...
;         if (nt * 256 + 128 < 5248) gemm_epilogue<EPI, 4>(ws, accB, rs, tokb, nt * 256 + 128, wm, wn, lr, lq, false);
.LBB0_1089:
	s_cmpk_lt_i32 s7, 0x1400
	s_cselect_b64 s[60:61], -1, 0
	s_ashr_i32 s7, s6, 31
	s_lshl_b64 s[6:7], s[6:7], 1
	s_add_u32 s6, s12, s6
	s_addc_u32 s7, s13, s7
	v_lshl_add_u64 v[66:67], v[172:173], 1, s[6:7]
	v_mov_b32_e32 v183, v12
	v_lshl_add_u64 v[66:67], v[66:67], 0, v[182:183]
	s_or_b64 s[8:9], s[38:39], s[60:61]
	v_mul_lo_u32 v71, s5, v215
	v_mul_lo_u32 v72, s4, v217
	v_mul_lo_u32 v70, s5, v214
	v_mul_lo_u32 v69, s5, v212
	v_mul_lo_u32 v68, s5, v13
	s_and_saveexec_b64 s[6:7], s[8:9]
	s_cbranch_execz .LBB0_1091
	s_waitcnt lgkmcnt(1)
	v_mov_b32_e32 v73, v180
	s_nop 0
	v_mul_f32_e32 v62, v62, v73
	v_mul_f32_e32 v63, v63, v73
	v_mul_f32_e32 v64, v64, v73
	v_mul_f32_e32 v65, v65, v73
	s_nop 0
	v_cvt_pk_bf16_f32 v62, v62, v63
	v_cvt_pk_bf16_f32 v63, v64, v65
	v_mad_u64_u32 v[64:65], s[8:9], s4, v215, 0
	v_add3_u32 v65, v65, v72, v71
	v_lshl_add_u64 v[64:65], v[64:65], 1, v[66:67]
	ds_bpermute_b32 v242, v250, v64
	ds_bpermute_b32 v243, v250, v65
	ds_bpermute_b32 v252, v250, v62
	ds_bpermute_b32 v253, v250, v63
	v_mov_b32_e32 v62, v181
	s_nop 0
	v_mul_f32_e32 v58, v58, v62
	v_mul_f32_e32 v59, v59, v62
	v_mul_f32_e32 v60, v60, v62
	v_mul_f32_e32 v61, v61, v62
	v_mul_lo_u32 v62, s4, v216
	v_cvt_pk_bf16_f32 v58, v58, v59
	v_cvt_pk_bf16_f32 v59, v60, v61
	v_mad_u64_u32 v[60:61], s[8:9], s4, v214, 0
	v_add3_u32 v61, v61, v62, v70
	v_lshl_add_u64 v[60:61], v[60:61], 1, v[66:67]
	ds_bpermute_b32 v244, v250, v60
	ds_bpermute_b32 v245, v250, v61
	ds_bpermute_b32 v254, v250, v58
	ds_bpermute_b32 v255, v250, v59
	s_waitcnt lgkmcnt(4)
	global_store_dwordx2 v[242:243], v[252:253], off
	s_waitcnt lgkmcnt(0)
	v_mov_b32_e32 v58, v178
	s_nop 0
	v_mul_f32_e32 v54, v54, v58
	v_mul_f32_e32 v55, v55, v58
	v_mul_f32_e32 v56, v56, v58
	v_mul_f32_e32 v57, v57, v58
	v_mul_lo_u32 v58, s4, v213
	v_cvt_pk_bf16_f32 v54, v54, v55
	v_cvt_pk_bf16_f32 v55, v56, v57
	v_mad_u64_u32 v[56:57], s[8:9], s4, v212, 0
	v_add3_u32 v57, v57, v58, v69
	v_lshl_add_u64 v[56:57], v[56:57], 1, v[66:67]
	ds_bpermute_b32 v246, v250, v56
	ds_bpermute_b32 v247, v250, v57
	ds_bpermute_b32 v252, v250, v54
	ds_bpermute_b32 v253, v250, v55
	s_waitcnt lgkmcnt(4)
	global_store_dwordx2 v[244:245], v[254:255], off
	v_mov_b32_e32 v54, v179
	s_nop 0
	v_mul_f32_e32 v50, v50, v54
	v_mul_f32_e32 v51, v51, v54
	v_mul_f32_e32 v52, v52, v54
	v_mul_f32_e32 v53, v53, v54
	v_mul_lo_u32 v54, s4, v169
	v_cvt_pk_bf16_f32 v50, v50, v51
	v_cvt_pk_bf16_f32 v51, v52, v53
	v_mad_u64_u32 v[52:53], s[8:9], s4, v13, 0
	v_add3_u32 v53, v53, v54, v68
	v_lshl_add_u64 v[52:53], v[52:53], 1, v[66:67]
	ds_bpermute_b32 v248, v250, v52
	ds_bpermute_b32 v249, v250, v53
	ds_bpermute_b32 v254, v250, v50
	ds_bpermute_b32 v255, v250, v51
	s_waitcnt lgkmcnt(4)
	global_store_dwordx2 v[246:247], v[252:253], off
	s_waitcnt lgkmcnt(0)
	global_store_dwordx2 v[248:249], v[254:255], off
; template <int EPI, int TI>
; __device__ __forceinline__ void gemm_epilogue(const WS& ws, const f32x4 (&acc)[4][TI], const float (&rs)[TI], int tok0, int n0,
;                                               int wm, int wn, int lr, int lq, bool dry) {
;     ...
;   if (EPI == EPI_E1) {
;     bf16_t* dst; int ld, c;
;     if (n0 < 1024) { dst = ws.XA; ld = 1024; c = n0; }
;     else if (n0 < 2048) { dst = ws.GA; ld = 1024; c = n0 - 1024; }
;     else if (n0 < 2560) { dst = ws.Q; ld = 512; c = n0 - 2048; }
;     else if (n0 < 3072) { dst = ws.K; ld = 512; c = n0 - 2560; }
;     else if (n0 < 4096) { dst = ws.V; ld = 1024; c = n0 - 3072; }
;     else if (n0 < 5120) { dst = ws.GB; ld = 1024; c = n0 - 4096; }
;     else { dst = ws.AD; ld = 16; c = 0; }
;     const bool isad = n0 >= 5120;
; #pragma unroll
;     for (int ni = 0; ni < 4; ++ni) {
;       if (isad && (wm != 0 || ni != 0)) continue;
; #pragma unroll
;       for (int ti = 0; ti < TI; ++ti) {
;         const f32x4 v = scale4(acc[ni][ti], rs[ti]);
;         u32x2 pk; pk.x = cvt_pk_bf16(v[0], v[1]); pk.y = cvt_pk_bf16(v[2], v[3]);
;         if (okr(ti)) *(u32x2*)(dst + (size_t)tokr(ti) * ld + c + wm * 64 + ni * 16 + 4 * lq) = pk;
;       }
;     }
; template <int EPI>
; __device__ __forceinline__ void gemm_wide(const WS& ws, const bf16_t* A, int lda, const bf16_t* __restrict__ W, int K, float invK,
;                                           int ntn, int ntiles, int bid) {
;     ...
;         if (nt * 256 + 128 < 5248) gemm_epilogue<EPI, 4>(ws, accB, rs, tokb, nt * 256 + 128, wm, wn, lr, lq, false);
.LBB0_1091:
	s_or_b64 exec, exec, s[6:7]
	s_andn2_b64 vcc, exec, s[60:61]
	s_cbranch_vccnz .LBB0_1093
	s_waitcnt lgkmcnt(1)
	v_mov_b32_e32 v50, v180
	s_nop 0
	v_mul_f32_e32 v46, v46, v50
	v_mul_f32_e32 v47, v47, v50
	v_mul_f32_e32 v48, v48, v50
	v_mul_f32_e32 v49, v49, v50
	s_nop 0
	v_cvt_pk_bf16_f32 v46, v46, v47
	v_cvt_pk_bf16_f32 v47, v48, v49
	v_mad_u64_u32 v[48:49], s[6:7], s4, v215, 0
	v_add3_u32 v49, v49, v72, v71
	v_lshl_add_u64 v[48:49], v[48:49], 1, v[66:67]
	ds_bpermute_b32 v242, v250, v48
	ds_bpermute_b32 v243, v250, v49
	ds_bpermute_b32 v252, v250, v46
	ds_bpermute_b32 v253, v250, v47
	v_mov_b32_e32 v46, v181
	s_nop 0
	v_mul_f32_e32 v42, v42, v46
	v_mul_f32_e32 v43, v43, v46
	v_mul_f32_e32 v44, v44, v46
	v_mul_f32_e32 v45, v45, v46
	v_mul_lo_u32 v46, s4, v216
	v_cvt_pk_bf16_f32 v42, v42, v43
	v_cvt_pk_bf16_f32 v43, v44, v45
	v_mad_u64_u32 v[44:45], s[6:7], s4, v214, 0
	v_add3_u32 v45, v45, v46, v70
	v_lshl_add_u64 v[44:45], v[44:45], 1, v[66:67]
	ds_bpermute_b32 v244, v250, v44
	ds_bpermute_b32 v245, v250, v45
	ds_bpermute_b32 v254, v250, v42
	ds_bpermute_b32 v255, v250, v43
	s_waitcnt lgkmcnt(4)
	global_store_dwordx2 v[242:243], v[252:253], off offset:32
	s_waitcnt lgkmcnt(0)
	v_mov_b32_e32 v42, v178
	s_nop 0
	v_mul_f32_e32 v38, v38, v42
	v_mul_f32_e32 v39, v39, v42
	v_mul_f32_e32 v40, v40, v42
	v_mul_f32_e32 v41, v41, v42
	v_mul_lo_u32 v42, s4, v213
	v_cvt_pk_bf16_f32 v38, v38, v39
	v_cvt_pk_bf16_f32 v39, v40, v41
	v_mad_u64_u32 v[40:41], s[6:7], s4, v212, 0
	v_add3_u32 v41, v41, v42, v69
	v_lshl_add_u64 v[40:41], v[40:41], 1, v[66:67]
	ds_bpermute_b32 v246, v250, v40
	ds_bpermute_b32 v247, v250, v41
	ds_bpermute_b32 v252, v250, v38
	ds_bpermute_b32 v253, v250, v39
	s_waitcnt lgkmcnt(4)
	global_store_dwordx2 v[244:245], v[254:255], off offset:32
	v_mov_b32_e32 v38, v179
	s_nop 0
	v_mul_f32_e32 v34, v34, v38
	v_mul_f32_e32 v35, v35, v38
	v_mul_f32_e32 v36, v36, v38
	v_mul_f32_e32 v37, v37, v38
	v_mul_lo_u32 v38, s4, v169
	v_cvt_pk_bf16_f32 v34, v34, v35
	v_cvt_pk_bf16_f32 v35, v36, v37
	v_mad_u64_u32 v[36:37], s[4:5], s4, v13, 0
	v_add3_u32 v37, v37, v38, v68
	v_lshl_add_u64 v[36:37], v[36:37], 1, v[66:67]
	v_mov_b32_e32 v13, v180
	ds_bpermute_b32 v248, v250, v36
	ds_bpermute_b32 v249, v250, v37
	ds_bpermute_b32 v254, v250, v34
	ds_bpermute_b32 v255, v250, v35
	s_waitcnt lgkmcnt(4)
	global_store_dwordx2 v[246:247], v[252:253], off offset:32
	s_nop 0
	v_mul_f32_e32 v30, v30, v13
	v_mul_f32_e32 v31, v31, v13
	v_mul_f32_e32 v32, v32, v13
	v_mul_f32_e32 v13, v33, v13
	s_nop 0
	v_cvt_pk_bf16_f32 v30, v30, v31
	v_cvt_pk_bf16_f32 v31, v32, v13
	v_mov_b32_e32 v13, v181
	ds_bpermute_b32 v252, v250, v30
	ds_bpermute_b32 v253, v250, v31
	s_waitcnt lgkmcnt(2)
	global_store_dwordx2 v[248:249], v[254:255], off offset:32
	s_nop 0
	v_mul_f32_e32 v26, v26, v13
	v_mul_f32_e32 v27, v27, v13
	v_mul_f32_e32 v28, v28, v13
	v_mul_f32_e32 v13, v29, v13
	s_nop 0
	v_cvt_pk_bf16_f32 v26, v26, v27
	v_cvt_pk_bf16_f32 v27, v28, v13
	v_mov_b32_e32 v13, v178
	ds_bpermute_b32 v254, v250, v26
	ds_bpermute_b32 v255, v250, v27
	s_waitcnt lgkmcnt(2)
	global_store_dwordx2 v[242:243], v[252:253], off offset:64
	s_nop 0
	v_mul_f32_e32 v22, v22, v13
	v_mul_f32_e32 v23, v23, v13
	v_mul_f32_e32 v24, v24, v13
	v_mul_f32_e32 v13, v25, v13
	s_nop 0
	v_cvt_pk_bf16_f32 v22, v22, v23
	v_cvt_pk_bf16_f32 v23, v24, v13
	v_mov_b32_e32 v13, v179
	ds_bpermute_b32 v252, v250, v22
	ds_bpermute_b32 v253, v250, v23
	s_waitcnt lgkmcnt(2)
	global_store_dwordx2 v[244:245], v[254:255], off offset:64
	s_nop 0
	v_mul_f32_e32 v18, v18, v13
	v_mul_f32_e32 v19, v19, v13
	v_mul_f32_e32 v20, v20, v13
	v_mul_f32_e32 v13, v21, v13
	s_nop 0
	v_cvt_pk_bf16_f32 v18, v18, v19
	v_cvt_pk_bf16_f32 v19, v20, v13
	ds_bpermute_b32 v254, v250, v18
	ds_bpermute_b32 v255, v250, v19
	s_waitcnt lgkmcnt(2)
	global_store_dwordx2 v[246:247], v[252:253], off offset:64
	s_nop 0
	v_mul_f32_e32 v13, v14, v180
	v_mul_f32_e32 v14, v15, v180
	v_mul_f32_e32 v15, v16, v180
	v_mul_f32_e32 v16, v17, v180
	s_nop 0
	v_cvt_pk_bf16_f32 v14, v13, v14
	v_cvt_pk_bf16_f32 v15, v15, v16
	ds_bpermute_b32 v252, v250, v14
	ds_bpermute_b32 v253, v250, v15
	s_waitcnt lgkmcnt(2)
	global_store_dwordx2 v[248:249], v[254:255], off offset:64
	s_nop 0
	v_mul_f32_e32 v8, v8, v181
	v_mul_f32_e32 v9, v9, v181
	v_mul_f32_e32 v10, v10, v181
	v_mul_f32_e32 v11, v11, v181
	s_nop 0
	v_cvt_pk_bf16_f32 v8, v8, v9
	v_cvt_pk_bf16_f32 v9, v10, v11
	ds_bpermute_b32 v254, v250, v8
	ds_bpermute_b32 v255, v250, v9
	s_waitcnt lgkmcnt(2)
	global_store_dwordx2 v[242:243], v[252:253], off offset:96
	s_nop 0
	v_mul_f32_e32 v4, v4, v178
	v_mul_f32_e32 v5, v5, v178
	v_mul_f32_e32 v6, v6, v178
	v_mul_f32_e32 v7, v7, v178
	s_nop 0
	v_cvt_pk_bf16_f32 v4, v4, v5
	v_cvt_pk_bf16_f32 v5, v6, v7
	ds_bpermute_b32 v252, v250, v4
	ds_bpermute_b32 v253, v250, v5
	s_waitcnt lgkmcnt(2)
	global_store_dwordx2 v[244:245], v[254:255], off offset:96
	s_nop 0
	v_mul_f32_e32 v0, v0, v179
	v_mul_f32_e32 v1, v1, v179
	v_mul_f32_e32 v2, v2, v179
	v_mul_f32_e32 v3, v3, v179
	s_nop 0
	v_cvt_pk_bf16_f32 v0, v0, v1
	v_cvt_pk_bf16_f32 v1, v2, v3
	ds_bpermute_b32 v254, v250, v0
	ds_bpermute_b32 v255, v250, v1
	s_waitcnt lgkmcnt(2)
	global_store_dwordx2 v[246:247], v[252:253], off offset:96
	s_waitcnt lgkmcnt(0)
	global_store_dwordx2 v[248:249], v[254:255], off offset:96
